# MLA loop: softmax of key block A interleaved with the QK MFMAs of key block B (PV_A after QK_B)
# baseline (speedup 1.0000x reference)
.LBB0_562:
	s_mul_i32 s0, s22, 0xa000
	v_add_u32_e32 v204, s0, v178
	v_add_u32_e32 v205, s0, v180
	v_add_u32_e32 v189, s0, v181
	v_add_u32_e32 v188, s0, v182
	ds_read_b128 v[208:211], v204
	ds_read_b128 v[212:215], v205
	ds_read_b128 v[216:219], v189
	ds_read_b128 v[220:223], v188
	v_add_u32_e32 v199, s0, v184
	v_add_u32_e32 v200, s0, v185
	v_add_u32_e32 v201, s0, v186
	v_add_u32_e32 v207, s0, v187
	ds_read_b128 v[224:227], v204 offset:128
	ds_read_b128 v[228:231], v205 offset:128
	ds_read_b128 v[232:235], v189 offset:128
	ds_read_b128 v[236:239], v188 offset:128
	s_waitcnt lgkmcnt(7)
	v_mfma_f32_32x32x16_bf16 v[96:111], v[208:211], v[112:115], v[64:79]
	ds_read_b128 v[240:243], v204 offset:256
	s_waitcnt lgkmcnt(7)
	v_mfma_f32_32x32x16_bf16 v[96:111], v[212:215], v[116:119], v[96:111]
	ds_read_b128 v[248:251], v205 offset:256
	s_waitcnt lgkmcnt(7)
	v_mfma_f32_32x32x16_bf16 v[96:111], v[216:219], v[120:123], v[96:111]
	ds_read_b128 v[208:211], v189 offset:256
	s_waitcnt lgkmcnt(7)
	v_mfma_f32_32x32x16_bf16 v[96:111], v[220:223], v[124:127], v[96:111]
	ds_read_b128 v[212:215], v188 offset:256
	s_waitcnt lgkmcnt(7)
	v_mfma_f32_32x32x16_bf16 v[96:111], v[224:227], v[128:131], v[96:111]
	ds_read_b128 v[216:219], v204 offset:12288
	s_waitcnt lgkmcnt(7)
	v_mfma_f32_32x32x16_bf16 v[96:111], v[228:231], v[132:135], v[96:111]
	ds_read_b128 v[220:223], v205 offset:12288
	s_waitcnt lgkmcnt(7)
	v_mfma_f32_32x32x16_bf16 v[96:111], v[232:235], v[136:139], v[96:111]
	ds_read_b128 v[224:227], v189 offset:12288
	s_waitcnt lgkmcnt(7)
	v_mfma_f32_32x32x16_bf16 v[96:111], v[236:239], v[140:143], v[96:111]
	ds_read_b128 v[228:231], v188 offset:12288
	s_waitcnt lgkmcnt(7)
	v_mfma_f32_32x32x16_bf16 v[96:111], v[240:243], v[144:147], v[96:111]
	ds_read_b128 v[232:235], v204 offset:12416
	s_waitcnt lgkmcnt(7)
	v_mfma_f32_32x32x16_bf16 v[96:111], v[248:251], v[148:151], v[96:111]
	ds_read_b128 v[236:239], v205 offset:12416
	s_waitcnt lgkmcnt(7)
	v_mfma_f32_32x32x16_bf16 v[96:111], v[208:211], v[152:155], v[96:111]
	ds_read_b128 v[240:243], v189 offset:12416
	s_waitcnt lgkmcnt(7)
	v_mfma_f32_32x32x16_bf16 v[96:111], v[212:215], v[156:159], v[96:111]
	ds_read_b128 v[248:251], v188 offset:12416
	s_add_i32 s0, s22, 1
	s_cmp_lg_u32 s22, 2
	s_cselect_b32 s22, s0, 0
	s_add_i32 s0, s15, 1
	s_cmp_lg_u32 s15, 2
	s_cselect_b32 s15, s0, 0
	s_nop 4
	v_max_f32_e32 v80, v97, v97
	v_max_f32_e32 v81, v96, v96
	v_max_f32_e32 v80, v81, v80
	v_max3_f32 v80, v80, v98, v99
	v_max3_f32 v80, v80, v100, v101
	v_max3_f32 v80, v80, v102, v103
	v_max3_f32 v80, v80, v104, v105
	v_max3_f32 v80, v80, v106, v107
	v_max3_f32 v80, v80, v108, v109
	v_max3_f32 v206, v80, v110, v111
	v_cmp_ge_f32_e32 vcc, s85, v206
	s_cmp_eq_u64 vcc, exec
	s_cbranch_scc1 .Lmla_a_norescale
	ds_bpermute_b32 v64, v183, v206
	s_waitcnt lgkmcnt(0)
	v_max3_f32 v64, v206, v64, 0
	v_exp_f32_e64 v66, -v64
	v_add_f32_e32 v165, v165, v64
	v_xor_b32_e32 v80, 0x80000000, v165
	v_pk_add_f32 v[96:97], v[96:97], v[64:65] op_sel_hi:[1,0] neg_lo:[0,1] neg_hi:[0,1]
	v_mul_f32_e32 v164, v164, v66
	v_pk_mul_f32 v[14:15], v[14:15], v[66:67] op_sel_hi:[1,0]
	v_pk_mul_f32 v[12:13], v[12:13], v[66:67] op_sel_hi:[1,0]
	v_pk_mul_f32 v[10:11], v[10:11], v[66:67] op_sel_hi:[1,0]
	v_pk_mul_f32 v[8:9], v[8:9], v[66:67] op_sel_hi:[1,0]
	v_pk_mul_f32 v[6:7], v[6:7], v[66:67] op_sel_hi:[1,0]
	v_pk_mul_f32 v[4:5], v[4:5], v[66:67] op_sel_hi:[1,0]
	v_pk_mul_f32 v[2:3], v[2:3], v[66:67] op_sel_hi:[1,0]
	v_pk_mul_f32 v[0:1], v[0:1], v[66:67] op_sel_hi:[1,0]
	v_pk_mul_f32 v[30:31], v[30:31], v[66:67] op_sel_hi:[1,0]
	v_pk_mul_f32 v[28:29], v[28:29], v[66:67] op_sel_hi:[1,0]
	v_pk_mul_f32 v[26:27], v[26:27], v[66:67] op_sel_hi:[1,0]
	v_pk_mul_f32 v[24:25], v[24:25], v[66:67] op_sel_hi:[1,0]
	v_pk_mul_f32 v[22:23], v[22:23], v[66:67] op_sel_hi:[1,0]
	v_pk_mul_f32 v[20:21], v[20:21], v[66:67] op_sel_hi:[1,0]
	v_pk_mul_f32 v[18:19], v[18:19], v[66:67] op_sel_hi:[1,0]
	v_pk_mul_f32 v[16:17], v[16:17], v[66:67] op_sel_hi:[1,0]
	v_pk_mul_f32 v[46:47], v[46:47], v[66:67] op_sel_hi:[1,0]
	v_pk_mul_f32 v[44:45], v[44:45], v[66:67] op_sel_hi:[1,0]
	v_pk_mul_f32 v[42:43], v[42:43], v[66:67] op_sel_hi:[1,0]
	v_pk_mul_f32 v[40:41], v[40:41], v[66:67] op_sel_hi:[1,0]
	v_pk_mul_f32 v[38:39], v[38:39], v[66:67] op_sel_hi:[1,0]
	v_pk_mul_f32 v[36:37], v[36:37], v[66:67] op_sel_hi:[1,0]
	v_pk_mul_f32 v[34:35], v[34:35], v[66:67] op_sel_hi:[1,0]
	v_pk_mul_f32 v[32:33], v[32:33], v[66:67] op_sel_hi:[1,0]
	v_pk_mul_f32 v[62:63], v[62:63], v[66:67] op_sel_hi:[1,0]
	v_pk_mul_f32 v[60:61], v[60:61], v[66:67] op_sel_hi:[1,0]
	v_pk_mul_f32 v[58:59], v[58:59], v[66:67] op_sel_hi:[1,0]
	v_pk_mul_f32 v[56:57], v[56:57], v[66:67] op_sel_hi:[1,0]
	v_pk_mul_f32 v[54:55], v[54:55], v[66:67] op_sel_hi:[1,0]
	v_pk_mul_f32 v[52:53], v[52:53], v[66:67] op_sel_hi:[1,0]
	v_pk_mul_f32 v[50:51], v[50:51], v[66:67] op_sel_hi:[1,0]
	v_pk_mul_f32 v[48:49], v[48:49], v[66:67] op_sel_hi:[1,0]
	v_pk_add_f32 v[98:99], v[98:99], v[64:65] op_sel_hi:[1,0] neg_lo:[0,1] neg_hi:[0,1]
	v_pk_add_f32 v[100:101], v[100:101], v[64:65] op_sel_hi:[1,0] neg_lo:[0,1] neg_hi:[0,1]
	v_pk_add_f32 v[102:103], v[102:103], v[64:65] op_sel_hi:[1,0] neg_lo:[0,1] neg_hi:[0,1]
	v_pk_add_f32 v[104:105], v[104:105], v[64:65] op_sel_hi:[1,0] neg_lo:[0,1] neg_hi:[0,1]
	v_pk_add_f32 v[106:107], v[106:107], v[64:65] op_sel_hi:[1,0] neg_lo:[0,1] neg_hi:[0,1]
	v_pk_add_f32 v[108:109], v[108:109], v[64:65] op_sel_hi:[1,0] neg_lo:[0,1] neg_hi:[0,1]
	v_pk_add_f32 v[110:111], v[110:111], v[64:65] op_sel_hi:[1,0] neg_lo:[0,1] neg_hi:[0,1]
	v_mov_b32_e32 v64, v80
	v_mov_b32_e32 v65, v80
	v_mov_b32_e32 v66, v80
	v_mov_b32_e32 v67, v80
	v_mov_b32_e32 v68, v80
	v_mov_b32_e32 v69, v80
	v_mov_b32_e32 v70, v80
	v_mov_b32_e32 v71, v80
	v_mov_b32_e32 v72, v80
	v_mov_b32_e32 v73, v80
	v_mov_b32_e32 v74, v80
	v_mov_b32_e32 v75, v80
	v_mov_b32_e32 v76, v80
	v_mov_b32_e32 v77, v80
	v_mov_b32_e32 v78, v80
	v_mov_b32_e32 v79, v80
	s_nop 1
.Lmla_a_norescale:
	s_waitcnt lgkmcnt(7)
	v_mfma_f32_32x32x16_bf16 v[80:95], v[216:219], v[112:115], v[64:79]
	ds_read_b128 v[208:211], v204 offset:12544
	v_exp_f32_e32 v96, v96
	v_exp_f32_e32 v97, v97
	v_exp_f32_e32 v98, v98
	v_exp_f32_e32 v99, v99
	s_waitcnt lgkmcnt(7)
	v_mfma_f32_32x32x16_bf16 v[80:95], v[220:223], v[116:119], v[80:95]
	ds_read_b128 v[212:215], v205 offset:12544
	v_add_f32_e32 v192, 0, v96
	v_exp_f32_e32 v193, v100
	v_add_f32_e32 v192, v97, v192
	s_waitcnt lgkmcnt(7)
	v_mfma_f32_32x32x16_bf16 v[80:95], v[224:227], v[120:123], v[80:95]
	ds_read_b128 v[216:219], v189 offset:12544
	v_add_f32_e32 v192, v98, v192
	v_add_f32_e32 v192, v99, v192
	v_exp_f32_e32 v101, v101
	s_waitcnt lgkmcnt(7)
	v_mfma_f32_32x32x16_bf16 v[80:95], v[228:231], v[124:127], v[80:95]
	ds_read_b128 v[220:223], v188 offset:12544
	v_add_f32_e32 v100, v193, v192
	v_exp_f32_e32 v192, v102
	v_exp_f32_e32 v194, v103
	v_exp_f32_e32 v195, v104
	s_waitcnt lgkmcnt(7)
	v_mfma_f32_32x32x16_bf16 v[80:95], v[232:235], v[128:131], v[80:95]
	ds_read_b128 v[224:227], v199 offset:24576
	v_add_f32_e32 v100, v101, v100
	v_exp_f32_e32 v198, v105
	v_add_f32_e32 v100, v192, v100
	s_waitcnt lgkmcnt(7)
	v_mfma_f32_32x32x16_bf16 v[80:95], v[236:239], v[132:135], v[80:95]
	ds_read_b128 v[228:231], v199 offset:28672
	v_exp_f32_e32 v106, v106
	v_add_f32_e32 v100, v194, v100
	v_exp_f32_e32 v107, v107
	s_waitcnt lgkmcnt(7)
	v_mfma_f32_32x32x16_bf16 v[80:95], v[240:243], v[136:139], v[80:95]
	ds_read_b128 v[232:235], v199 offset:32768
	v_add_f32_e32 v100, v195, v100
	v_exp_f32_e32 v108, v108
	v_add_f32_e32 v100, v198, v100
	v_exp_f32_e32 v109, v109
	s_waitcnt lgkmcnt(7)
	v_mfma_f32_32x32x16_bf16 v[80:95], v[248:251], v[140:143], v[80:95]
	ds_read_b128 v[236:239], v199 offset:36864
	v_add_f32_e32 v100, v106, v100
	v_add_f32_e32 v100, v107, v100
	v_add_f32_e32 v100, v108, v100
	s_waitcnt lgkmcnt(7)
	v_mfma_f32_32x32x16_bf16 v[80:95], v[208:211], v[144:147], v[80:95]
	ds_read_b128 v[240:243], v200 offset:24576
	v_cvt_pk_bf16_f32 v104, v193, v101
	v_add_f32_e32 v100, v109, v100
	v_cvt_pk_bf16_f32 v102, v96, v97
	s_waitcnt lgkmcnt(7)
	v_mfma_f32_32x32x16_bf16 v[80:95], v[212:215], v[148:151], v[80:95]
	ds_read_b128 v[248:251], v200 offset:28672
	v_cvt_pk_bf16_f32 v103, v98, v99
	v_cvt_pk_bf16_f32 v97, v106, v107
	v_cvt_pk_bf16_f32 v98, v108, v109
	v_cvt_pk_bf16_f32 v105, v192, v194
	s_waitcnt lgkmcnt(7)
	v_mfma_f32_32x32x16_bf16 v[80:95], v[216:219], v[152:155], v[80:95]
	ds_read_b128 v[208:211], v200 offset:32768
	v_exp_f32_e32 v110, v110
	v_exp_f32_e32 v111, v111
	v_cvt_pk_bf16_f32 v96, v195, v198
	s_waitcnt lgkmcnt(7)
	v_mfma_f32_32x32x16_bf16 v[80:95], v[220:223], v[156:159], v[80:95]
	ds_read_b128 v[212:215], v200 offset:36864
	v_cvt_pk_bf16_f32 v99, v110, v111
	v_add_f32_e32 v100, v110, v100
	v_add_f32_e32 v100, v111, v100
	s_waitcnt lgkmcnt(7)
	v_mfma_f32_32x32x16_bf16 v[48:63], v[224:227], v[102:105], v[48:63]
	ds_read_b128 v[216:219], v201 offset:24576
	s_waitcnt lgkmcnt(7)
	v_mfma_f32_32x32x16_bf16 v[32:47], v[228:231], v[102:105], v[32:47]
	ds_read_b128 v[220:223], v201 offset:28672
	s_waitcnt lgkmcnt(7)
	v_mfma_f32_32x32x16_bf16 v[16:31], v[232:235], v[102:105], v[16:31]
	ds_read_b128 v[224:227], v201 offset:32768
	s_waitcnt lgkmcnt(7)
	v_mfma_f32_32x32x16_bf16 v[0:15], v[236:239], v[102:105], v[0:15]
	ds_read_b128 v[228:231], v201 offset:36864
	s_waitcnt lgkmcnt(7)
	v_mfma_f32_32x32x16_bf16 v[48:63], v[240:243], v[96:99], v[48:63]
	ds_read_b128 v[232:235], v207 offset:24576
	s_waitcnt lgkmcnt(7)
	v_mfma_f32_32x32x16_bf16 v[32:47], v[248:251], v[96:99], v[32:47]
	ds_read_b128 v[236:239], v207 offset:28672
	s_waitcnt lgkmcnt(7)
	v_mfma_f32_32x32x16_bf16 v[16:31], v[208:211], v[96:99], v[16:31]
	ds_read_b128 v[240:243], v207 offset:32768
	s_waitcnt lgkmcnt(7)
	v_mfma_f32_32x32x16_bf16 v[0:15], v[212:215], v[96:99], v[0:15]
	ds_read_b128 v[248:251], v207 offset:36864
	v_lshl_add_u64 v[166:167], v[166:167], 0, s[66:67]
	v_lshl_add_u64 v[168:169], v[168:169], 0, v[162:163]
	v_lshl_add_u64 v[170:171], v[170:171], 0, v[160:161]
	v_lshl_add_u64 v[172:173], v[172:173], 0, v[176:177]
	s_nop 1
	v_max_f32_e32 v96, v81, v81
	v_max_f32_e32 v97, v80, v80
	v_max_f32_e32 v96, v97, v96
	v_max3_f32 v96, v96, v82, v83
	v_max3_f32 v96, v96, v84, v85
	v_max3_f32 v96, v96, v86, v87
	v_max3_f32 v96, v96, v88, v89
	v_max3_f32 v96, v96, v90, v91
	v_max3_f32 v96, v96, v92, v93
	v_max3_f32 v97, v96, v94, v95
	v_cmp_ge_f32_e32 vcc, s85, v97
	v_add_f32_e32 v96, v164, v100
	s_cmp_eq_u64 vcc, exec
	s_cbranch_scc1 .Lmla_b_norescale
	ds_bpermute_b32 v64, v183, v97
	s_waitcnt lgkmcnt(0)
	v_max3_f32 v66, v97, v64, 0
	v_exp_f32_e64 v68, -v66
	v_add_f32_e32 v165, v165, v66
	v_xor_b32_e32 v64, 0x80000000, v165
	v_pk_add_f32 v[80:81], v[80:81], v[66:67] op_sel_hi:[1,0] neg_lo:[0,1] neg_hi:[0,1]
	v_pk_mul_f32 v[62:63], v[62:63], v[68:69] op_sel_hi:[1,0]
	v_pk_mul_f32 v[60:61], v[60:61], v[68:69] op_sel_hi:[1,0]
	v_pk_mul_f32 v[58:59], v[58:59], v[68:69] op_sel_hi:[1,0]
	v_pk_mul_f32 v[56:57], v[56:57], v[68:69] op_sel_hi:[1,0]
	v_pk_mul_f32 v[54:55], v[54:55], v[68:69] op_sel_hi:[1,0]
	v_pk_mul_f32 v[52:53], v[52:53], v[68:69] op_sel_hi:[1,0]
	v_pk_mul_f32 v[50:51], v[50:51], v[68:69] op_sel_hi:[1,0]
	v_pk_mul_f32 v[48:49], v[48:49], v[68:69] op_sel_hi:[1,0]
	v_pk_mul_f32 v[46:47], v[46:47], v[68:69] op_sel_hi:[1,0]
	v_pk_mul_f32 v[44:45], v[44:45], v[68:69] op_sel_hi:[1,0]
	v_pk_mul_f32 v[42:43], v[42:43], v[68:69] op_sel_hi:[1,0]
	v_pk_mul_f32 v[40:41], v[40:41], v[68:69] op_sel_hi:[1,0]
	v_pk_mul_f32 v[38:39], v[38:39], v[68:69] op_sel_hi:[1,0]
	v_pk_mul_f32 v[36:37], v[36:37], v[68:69] op_sel_hi:[1,0]
	v_pk_mul_f32 v[34:35], v[34:35], v[68:69] op_sel_hi:[1,0]
	v_pk_mul_f32 v[32:33], v[32:33], v[68:69] op_sel_hi:[1,0]
	v_pk_mul_f32 v[30:31], v[30:31], v[68:69] op_sel_hi:[1,0]
	v_pk_mul_f32 v[28:29], v[28:29], v[68:69] op_sel_hi:[1,0]
	v_pk_mul_f32 v[26:27], v[26:27], v[68:69] op_sel_hi:[1,0]
	v_pk_mul_f32 v[24:25], v[24:25], v[68:69] op_sel_hi:[1,0]
	v_pk_mul_f32 v[22:23], v[22:23], v[68:69] op_sel_hi:[1,0]
	v_pk_mul_f32 v[20:21], v[20:21], v[68:69] op_sel_hi:[1,0]
	v_pk_mul_f32 v[18:19], v[18:19], v[68:69] op_sel_hi:[1,0]
	v_pk_mul_f32 v[16:17], v[16:17], v[68:69] op_sel_hi:[1,0]
	v_pk_mul_f32 v[14:15], v[14:15], v[68:69] op_sel_hi:[1,0]
	v_pk_mul_f32 v[12:13], v[12:13], v[68:69] op_sel_hi:[1,0]
	v_pk_mul_f32 v[10:11], v[10:11], v[68:69] op_sel_hi:[1,0]
	v_pk_mul_f32 v[8:9], v[8:9], v[68:69] op_sel_hi:[1,0]
	v_pk_mul_f32 v[6:7], v[6:7], v[68:69] op_sel_hi:[1,0]
	v_pk_mul_f32 v[4:5], v[4:5], v[68:69] op_sel_hi:[1,0]
	v_pk_mul_f32 v[2:3], v[2:3], v[68:69] op_sel_hi:[1,0]
	v_pk_mul_f32 v[0:1], v[0:1], v[68:69] op_sel_hi:[1,0]
	v_pk_add_f32 v[82:83], v[82:83], v[66:67] op_sel_hi:[1,0] neg_lo:[0,1] neg_hi:[0,1]
	v_pk_add_f32 v[84:85], v[84:85], v[66:67] op_sel_hi:[1,0] neg_lo:[0,1] neg_hi:[0,1]
	v_pk_add_f32 v[86:87], v[86:87], v[66:67] op_sel_hi:[1,0] neg_lo:[0,1] neg_hi:[0,1]
	v_pk_add_f32 v[88:89], v[88:89], v[66:67] op_sel_hi:[1,0] neg_lo:[0,1] neg_hi:[0,1]
	v_pk_add_f32 v[90:91], v[90:91], v[66:67] op_sel_hi:[1,0] neg_lo:[0,1] neg_hi:[0,1]
	v_pk_add_f32 v[92:93], v[92:93], v[66:67] op_sel_hi:[1,0] neg_lo:[0,1] neg_hi:[0,1]
	v_pk_add_f32 v[94:95], v[94:95], v[66:67] op_sel_hi:[1,0] neg_lo:[0,1] neg_hi:[0,1]
	v_mul_f32_e32 v96, v96, v68
	v_mov_b32_e32 v65, v64
	v_mov_b32_e32 v66, v64
	v_mov_b32_e32 v67, v64
	v_mov_b32_e32 v68, v64
	v_mov_b32_e32 v69, v64
	v_mov_b32_e32 v70, v64
	v_mov_b32_e32 v71, v64
	v_mov_b32_e32 v72, v64
	v_mov_b32_e32 v73, v64
	v_mov_b32_e32 v74, v64
	v_mov_b32_e32 v75, v64
	v_mov_b32_e32 v76, v64
	v_mov_b32_e32 v77, v64
	v_mov_b32_e32 v78, v64
	v_mov_b32_e32 v79, v64
